# in_proj phase: small pieces redistributed so the 36 workgroups with only 3 big units take 8-9 pieces and the 220 with 4 units take 1
# speedup vs baseline: 1.0007x; 1.0007x over previous
.LBB0_1208:
	s_abs_i32 s0, s68
	v_cvt_f32_u32_e32 v2, s0
	s_and_b32 s1, s8, 7
	s_ashr_i32 s2, s68, 3
	s_mul_i32 s1, s1, s2
	v_rcp_iflag_f32_e32 v2, v2
	s_sub_i32 s2, 0, s0
	s_ashr_i32 s3, s8, 3
	s_mov_b32 s83, 0xd000
	v_mul_f32_e32 v2, 0x4f7ffffe, v2
	v_cvt_u32_f32_e32 v2, v2
	s_movk_i32 s84, 0x5800
	v_readfirstlane_b32 s4, v2
	s_mul_i32 s2, s2, s4
	s_mul_hi_u32 s2, s4, s2
	s_add_i32 s4, s4, s2
	s_mul_hi_u32 s2, s85, s4
	s_mul_i32 s2, s2, s0
	s_sub_i32 s2, s85, s2
	s_sub_i32 s5, s2, s0
	s_cmp_ge_u32 s2, s0
	s_cselect_b32 s2, s5, s2
	s_sub_i32 s5, s2, s0
	s_cmp_ge_u32 s2, s0
	s_cselect_b32 s2, s5, s2
	s_add_i32 s3, s3, s68
	s_add_i32 s3, s3, s1
	s_sub_i32 s1, s3, s2
	s_ashr_i32 s2, s1, 31
	s_abs_i32 s1, s1
	s_mul_hi_u32 s3, s1, s4
	s_mul_i32 s3, s3, s0
	s_sub_i32 s1, s1, s3
	s_sub_i32 s3, s1, s0
	s_cmp_ge_u32 s1, s0
	s_cselect_b32 s1, s3, s1
	s_sub_i32 s3, s1, s0
	s_cmp_ge_u32 s1, s0
	s_cselect_b32 s0, s3, s1
	s_xor_b32 s0, s0, s2
	s_sub_i32 s33, s0, s2
	s_cmp_lg_u32 s70, 1
	s_cbranch_scc1 .Lsp_init_done
	v_readlane_b32 s0, v254, 62
	s_cmpk_lg_u32 s0, 0x100
	s_cbranch_scc1 .Lsp_init_done
	v_readlane_b32 s0, v255, 2
	s_cmpk_lt_u32 s0, 0xdc
	s_cbranch_scc1 .Lsp_long
	s_sub_i32 s0, s0, 0xdc
	s_lshl_b32 s33, s0, 3
	s_mov_b32 s32, 1
	s_branch .Lsp_init_done
.Lsp_long:
	s_add_i32 s33, s0, 0x120
	s_mov_b32 s32, 100
.Lsp_init_done:
	v_readlane_b32 s0, v255, 28
	s_cmp_ge_i32 s33, s0
	s_movk_i32 s85, 0x7fd
	s_cbranch_scc1 .LBB0_1293
	s_cmp_lg_u32 s70, 1
	s_cselect_b64 s[4:5], -1, 0
	s_cmp_eq_u32 s70, 1
	v_lshlrev_b32_e32 v2, 3, v1
	s_cselect_b64 vcc, -1, 0
	v_and_b32_e32 v2, 24, v2
	v_and_b32_e32 v3, 4, v174
	s_and_b64 s[0:1], vcc, exec
	v_ashrrev_i32_e32 v132, 4, v174
	v_or3_b32 v2, v2, v3, v164
	s_cselect_b32 s36, 0, 0x4000
	s_lshr_b32 s37, s7, 3
	v_lshlrev_b32_e32 v3, 8, v132
	v_lshlrev_b32_e32 v4, 4, v1
	s_waitcnt lgkmcnt(0)
	s_add_u32 s38, s10, 0x1bd3d800
	v_add3_u32 v150, 0, v3, v4
	v_cvt_f32_u32_e32 v4, s82
	s_addc_u32 s39, s11, 0
	s_add_u32 s40, s10, 0x700000
	v_readlane_b32 s0, v255, 38
	v_lshrrev_b32_e32 v5, 1, v132
	s_addc_u32 s41, s11, 0
	s_lshl_b32 s0, s0, 13
	v_lshlrev_b32_e32 v3, 2, v132
	v_and_b32_e32 v5, 12, v5
	s_add_i32 s0, s0, 0
	v_and_or_b32 v151, v3, 16, v5
	v_rcp_iflag_f32_e32 v3, v4
	s_add_u32 s6, s10, 0x2400000
	s_addc_u32 s7, s11, 0
	s_add_u32 s8, s10, 0x1bd0c000
	s_addc_u32 s9, s11, 0
	v_mul_f32_e32 v3, 0x4f7ffffe, v3
	s_add_u32 s26, s10, 0xb508000
	v_cvt_u32_f32_e32 v3, v3
	s_addc_u32 s27, s11, 0
	s_add_u32 s2, s10, s24
	s_addc_u32 s3, s11, s25
	v_ashrrev_i32_e32 v133, 31, v132
	v_lshl_add_u64 v[134:135], v[132:133], 2, s[2:3]
	s_sub_i32 s2, 0, s82
	v_readfirstlane_b32 s3, v3
	s_mul_i32 s2, s2, s3
	v_cndmask_b32_e32 v27, v2, v27, vcc
	v_lshl_add_u32 v2, v1, 8, s0
	s_mul_hi_u32 s2, s3, s2
	v_cmp_eq_u32_e64 s[0:1], 0, v1
	s_add_i32 s42, s3, s2
	v_and_b32_e32 v138, 48, v174
	v_mov_b32_e32 v139, v26
	v_add_u32_e32 v133, v2, v136
	s_branch .LBB0_1212

.LBB0_1211:
	s_cmp_eq_u32 s32, 0
	s_cbranch_scc1 .Lsp_std
	s_cmp_eq_u32 s32, 100
	s_cbranch_scc1 .Lsp_exit
	s_add_i32 s32, s32, 1
	s_cmpk_le_u32 s32, 8
	s_cbranch_scc0 .Lsp_ninth
	s_add_i32 s33, s33, 1
	s_branch .Lsp_next
.Lsp_ninth:
	s_cmpk_gt_u32 s32, 9
	s_cbranch_scc1 .Lsp_exit
	v_readlane_b32 s2, v255, 2
	s_sub_i32 s2, s2, 0xdc
	s_cmpk_gt_u32 s2, 3
	s_cbranch_scc1 .Lsp_exit
	s_add_i32 s33, s2, 0x1fc
	s_branch .Lsp_next
.Lsp_exit:
	s_mov_b32 s33, 0x7fffffff
	s_branch .Lsp_next

.Lsp_next:
	v_readlane_b32 s2, v255, 28
	s_cmp_lt_i32 s33, s2
	s_waitcnt lgkmcnt(0)
	s_barrier
	s_cbranch_scc0 .LBB0_1293

.LBB0_1293:
	s_mov_b32 s32, 0
	s_cmp_eq_u32 s70, 9
	v_readlane_b32 s2, v255, 2
	s_cselect_b64 s[0:1], -1, 0
	v_readlane_b32 s3, v255, 3
	s_mov_b32 s4, s2
	s_bitcmp0_b32 s2, 0
	s_cselect_b64 s[2:3], -1, 0
	s_cmpk_lt_i32 s4, 0x200
	s_cselect_b64 s[4:5], -1, 0
	s_and_b64 s[0:1], s[2:3], s[0:1]
	s_and_b64 s[0:1], s[0:1], s[4:5]
	v_readlane_b32 s50, v254, 50
	v_readlane_b32 s52, v254, 52
	v_readlane_b32 s80, v254, 54
	s_andn2_b64 vcc, exec, s[0:1]
	v_readlane_b32 s51, v254, 51
	v_readlane_b32 s53, v254, 53
	v_readlane_b32 s81, v254, 55
	s_movk_i32 s49, 0x41ff
	s_movk_i32 s68, 0x7f0
	s_movk_i32 s69, 0x5000
	s_mov_b32 s82, 0xb000
	s_cbranch_vccnz .LBB0_1328
	v_ashrrev_i32_e32 v3, 8, v174
	s_movk_i32 s0, 0x100
	v_cmp_gt_u32_e64 s[4:5], s0, v174
	v_lshl_add_u32 v5, v3, 12, 0
	s_movk_i32 s0, 0x3000
	v_mad_i32_i24 v3, v3, s0, v5
	s_waitcnt lgkmcnt(0)
	s_add_u32 s0, s10, 0xb508000
	v_and_b32_e32 v2, 63, v174
	v_bfe_u32 v4, v174, 6, 2
	s_addc_u32 s1, s11, 0
	v_lshrrev_b32_e32 v6, 1, v174
	v_lshlrev_b32_e32 v148, 2, v2
	v_and_b32_e32 v150, 24, v6
	v_cmp_gt_u32_e64 s[8:9], 16, v2
	v_lshlrev_b32_e32 v6, 10, v4
	v_lshlrev_b32_e32 v2, 4, v2
	s_add_u32 s2, s10, 0xf608000
	v_lshl_add_u32 v151, v4, 8, v5
	v_add3_u32 v157, v5, v6, v2
	v_lshlrev_b32_e32 v5, 12, v4
	s_addc_u32 s3, s11, 0
	v_readlane_b32 s10, v254, 62
	v_lshlrev_b32_e32 v27, 6, v4
	v_cmp_gt_u32_e64 s[6:7], 4, v1
	v_or_b32_e32 v149, 0x4000, v1
	v_lshl_add_u32 v156, v1, 2, v151
	v_add3_u32 v158, v3, v5, v2
	v_add3_u32 v159, v3, v6, v2
	v_or_b32_e32 v160, 0x4000, v4
	s_lshl_b32 s18, s10, 1
	v_readlane_b32 s12, v255, 2
	v_readlane_b32 s11, v254, 63
	v_readlane_b32 s13, v255, 3
	s_branch .LBB0_1296
